# PEER expert phase rewritten: 4 tokens pooled per wave, per-token sorted lists merged by groups, LDS-resident accumulators, leader phase pointer
# speedup vs baseline: 1.1146x; 1.0460x over previous
.LBB0_471:
	v_lshl_add_u64 v[62:63], s[36:37], 0, v[58:59]
	v_lshlrev_b64 v[0:1], 11, v[62:63]
	v_lshlrev_b64 v[12:13], 9, v[62:63]
	v_lshl_add_u64 v[0:1], s[16:17], 0, v[0:1]
	v_lshlrev_b32_e32 v10, 5, v60
	v_mov_b32_e32 v11, v57
	v_lshl_or_b32 v12, v60, 2, v12
	v_lshl_add_u64 v[4:5], v[0:1], 0, v[10:11]
	v_lshl_add_u64 v[14:15], s[12:13], 0, v[12:13]
	v_or_b32_e32 v16, 0x100, v12
	v_mov_b32_e32 v17, v13
	s_barrier
	s_nop 0
	v_lshl_add_u64 v[18:19], s[12:13], 0, v[16:17]
	v_lshl_add_u64 v[12:13], s[14:15], 0, v[12:13]
	v_lshl_add_u64 v[16:17], s[14:15], 0, v[16:17]
	v_and_b32_e32 v8, 2, v8
	v_cmp_eq_u32_e64 s[6:7], 0, v8
	v_xor_b32_e32 v8, 4, v61
	v_cmp_lt_i32_e32 vcc, v8, v107
	v_readlane_b32 s76, v254, 32
	v_lshl_add_u64 v[64:65], s[18:19], 0, v[56:57]
	v_cndmask_b32_e32 v8, v61, v8, vcc
	v_lshlrev_b32_e32 v124, 2, v8
	v_xor_b32_e32 v8, 8, v61
	v_cmp_lt_i32_e32 vcc, v8, v107
	v_lshl_add_u64 v[66:67], s[20:21], 0, v[56:57]
	v_lshlrev_b32_e32 v56, 6, v60
	v_cndmask_b32_e32 v8, v61, v8, vcc
	v_lshlrev_b32_e32 v125, 2, v8
	v_xor_b32_e32 v8, 16, v61
	v_cmp_lt_i32_e32 vcc, v8, v107
	v_readlane_b32 s78, v254, 34
	v_readlane_b32 s79, v254, 35
	v_cndmask_b32_e32 v8, v61, v8, vcc
	v_lshlrev_b32_e32 v126, 2, v8
	v_xor_b32_e32 v8, 32, v61
	v_cmp_lt_i32_e32 vcc, v8, v107
	s_mov_b32 s23, 0
	v_cmp_eq_u32_e64 s[8:9], 0, v9
	v_cndmask_b32_e32 v8, v61, v8, vcc
	v_lshlrev_b32_e32 v127, 2, v8
	v_cmp_eq_u32_e64 s[10:11], 1, v9
	v_lshl_add_u64 v[68:69], s[78:79], 0, v[56:57]
	v_lshl_add_u64 v[70:71], s[16:17], 0, v[10:11]
	v_readlane_b32 s77, v254, 33
	s_branch .LBB0_480

.LBB0_598:
	s_barrier
	v_and_b32_e32 v249, 2, v60
	v_cmp_eq_u32_e64 s[6:7], 0, v249
	v_and_b32_e32 v249, 1, v60
	v_cmp_eq_u32_e64 s[0:1], 0, v249
	v_mov_b32_e32 v253, 0
	v_mov_b32_e32 v147, 0
	v_mov_b32_e32 v148, 0
	v_mov_b32_e32 v244, 0
	v_lshlrev_b32_e32 v248, 10, v58
	v_lshl_add_u32 v248, v60, 4, v248
	s_and_b32 s2, s96, 7
	s_lshl_b32 s2, s2, 7
	s_add_u32 s2, s2, s44
	s_addc_u32 s3, s45, 0
	s_add_u32 s2, s2, 0xffff8100
	s_addc_u32 s3, s3, -1
	v_mov_b32_e32 v246, s2
	v_mov_b32_e32 v247, s3
	s_mov_b32 s23, 0
.Lxp_sweep:
	v_readfirstlane_b32 s2, v58
	s_lshr_b32 s3, s23, 2
	s_lshl_b32 s3, s3, 6
	s_add_i32 s2, s2, s3
	s_and_b32 s3, s23, 3
	s_lshl_b32 s3, s3, 2
	s_add_i32 s2, s2, s3
	s_add_i32 s2, s2, s34
	s_sub_i32 s32, s2, 64
	s_lshl_b32 s2, s32, 11
	s_add_u32 s36, s92, s2
	s_addc_u32 s37, s93, 0
	s_mov_b32 s25, 0
	v_mov_b32_e32 v243, 0
.Lxp_tok:
	s_add_i32 s2, s32, s25
	s_lshl_b32 s3, s2, 11
	v_lshl_add_u32 v249, v60, 5, s3
	global_load_dwordx4 v[0:3], v249, s[16:17] offset:16
	global_load_dwordx4 v[4:7], v249, s[16:17]
	s_lshl_b32 s3, s2, 9
	v_lshl_add_u32 v250, v60, 2, s3
	global_load_dword v59, v250, s[12:13]
	global_load_dword v89, v250, s[12:13] offset:256
	global_load_dword v128, v250, s[14:15]
	global_load_dword v129, v250, s[14:15] offset:256
	s_lshl_b32 s2, s2, 2
	s_add_u32 s2, s41, s2
	s_addc_u32 s3, s43, 0
	global_load_dword v40, v253, s[2:3]
	s_lshl_b32 s2, s25, 12
	v_add_u32_e32 v251, s2, v248
	v_mov_b32_e32 v8, 0
	v_mov_b32_e32 v9, 0
	v_mov_b32_e32 v10, 0
	v_mov_b32_e32 v11, 0
	ds_write_b128 v251, v[8:11]
	ds_write_b128 v251, v[8:11] offset:1024
	ds_write_b128 v251, v[8:11] offset:2048
	ds_write_b128 v251, v[8:11] offset:3072
	s_waitcnt vmcnt(0)
	v_lshlrev_b32_e32 v84, 16, v4
	v_and_b32_e32 v85, 0xffff0000, v4
	v_lshlrev_b32_e32 v86, 16, v5
	v_and_b32_e32 v87, 0xffff0000, v5
	v_lshlrev_b32_e32 v80, 16, v6
	v_and_b32_e32 v81, 0xffff0000, v6
	v_lshlrev_b32_e32 v82, 16, v7
	v_and_b32_e32 v83, 0xffff0000, v7
	v_lshlrev_b32_e32 v76, 16, v0
	v_and_b32_e32 v77, 0xffff0000, v0
	v_lshlrev_b32_e32 v78, 16, v1
	v_and_b32_e32 v79, 0xffff0000, v1
	v_lshlrev_b32_e32 v72, 16, v2
	v_and_b32_e32 v73, 0xffff0000, v2
	v_lshlrev_b32_e32 v74, 16, v3
	v_and_b32_e32 v75, 0xffff0000, v3
	v_max3_f32 v0, |v84|, 0, |v85|
	v_max3_f32 v0, v0, |v86|, |v87|
	v_max3_f32 v0, v0, |v80|, |v81|
	v_max3_f32 v0, v0, |v82|, |v83|
	v_max3_f32 v0, v0, |v76|, |v77|
	v_max3_f32 v0, v0, |v78|, |v79|
	v_max3_f32 v0, v0, |v72|, |v73|
	v_max3_f32 v0, v0, |v74|, |v75|
	ds_bpermute_b32 v1, v127, v0
	s_waitcnt lgkmcnt(0)
	v_max_f32_e32 v1, v1, v1
	v_max_f32_e32 v0, v0, v1
	ds_bpermute_b32 v1, v126, v0
	s_waitcnt lgkmcnt(0)
	v_max_f32_e32 v1, v1, v1
	v_max_f32_e32 v0, v0, v1
	ds_bpermute_b32 v1, v125, v0
	s_waitcnt lgkmcnt(0)
	v_max_f32_e32 v1, v1, v1
	v_max_f32_e32 v0, v0, v1
	ds_bpermute_b32 v1, v124, v0
	s_waitcnt lgkmcnt(0)
	v_max_f32_e32 v1, v1, v1
	v_max_f32_e32 v0, v0, v1
	ds_bpermute_b32 v1, v123, v0
	s_waitcnt lgkmcnt(0)
	v_max_f32_e32 v1, v1, v1
	v_max_f32_e32 v0, v0, v1
	ds_bpermute_b32 v1, v122, v0
	s_waitcnt lgkmcnt(0)
	v_max_f32_e32 v1, v1, v1
	v_max_f32_e32 v0, v0, v1
	v_max_f32_e32 v16, s63, v0
	v_div_scale_f32 v17, s[2:3], v16, v16, s64
	v_rcp_f32_e32 v18, v17
	s_nop 0
	v_fma_f32 v8, -v17, v18, 1.0
	v_fmac_f32_e32 v18, v8, v18
	v_div_scale_f32 v8, vcc, s64, v16, s64
	v_mul_f32_e32 v9, v8, v18
	v_fma_f32 v10, -v17, v9, v8
	v_fmac_f32_e32 v9, v10, v18
	v_fma_f32 v8, -v17, v9, v8
	s_nop 0
	v_div_fmas_f32 v8, v8, v18, v9
	v_div_fixup_f32 v41, v8, v16, s64
	v_mul_f32_e32 v42, 0x3c010204, v16
	v_mul_f32_e32 v43, v40, v42
	v_cmp_eq_u32_e32 vcc, s25, v60
	s_nop 1
	v_cndmask_b32_e32 v244, v244, v43, vcc
	v_mul_f32_e32 v8, v41, v84
	v_rndne_f32_e32 v8, v8
	v_cvt_i32_f32_e32 v8, v8
	v_mul_f32_e32 v9, v41, v85
	v_rndne_f32_e32 v9, v9
	v_cvt_i32_f32_e32 v9, v9
	v_mul_f32_e32 v10, v41, v86
	v_rndne_f32_e32 v10, v10
	v_cvt_i32_f32_e32 v10, v10
	v_mul_f32_e32 v11, v41, v87
	v_rndne_f32_e32 v11, v11
	v_cvt_i32_f32_e32 v11, v11
	v_and_b32_e32 v8, 0xff, v8
	v_and_b32_e32 v9, 0xff, v9
	v_and_b32_e32 v10, 0xff, v10
	v_lshl_or_b32 v8, v9, 8, v8
	v_lshl_or_b32 v8, v10, 16, v8
	v_lshl_or_b32 v133, v11, 24, v8
	v_mul_f32_e32 v8, v41, v80
	v_rndne_f32_e32 v8, v8
	v_cvt_i32_f32_e32 v8, v8
	v_mul_f32_e32 v9, v41, v81
	v_rndne_f32_e32 v9, v9
	v_cvt_i32_f32_e32 v9, v9
	v_mul_f32_e32 v10, v41, v82
	v_rndne_f32_e32 v10, v10
	v_cvt_i32_f32_e32 v10, v10
	v_mul_f32_e32 v11, v41, v83
	v_rndne_f32_e32 v11, v11
	v_cvt_i32_f32_e32 v11, v11
	v_and_b32_e32 v8, 0xff, v8
	v_and_b32_e32 v9, 0xff, v9
	v_and_b32_e32 v10, 0xff, v10
	v_lshl_or_b32 v8, v9, 8, v8
	v_lshl_or_b32 v8, v10, 16, v8
	v_lshl_or_b32 v134, v11, 24, v8
	v_mul_f32_e32 v8, v41, v76
	v_rndne_f32_e32 v8, v8
	v_cvt_i32_f32_e32 v8, v8
	v_mul_f32_e32 v9, v41, v77
	v_rndne_f32_e32 v9, v9
	v_cvt_i32_f32_e32 v9, v9
	v_mul_f32_e32 v10, v41, v78
	v_rndne_f32_e32 v10, v10
	v_cvt_i32_f32_e32 v10, v10
	v_mul_f32_e32 v11, v41, v79
	v_rndne_f32_e32 v11, v11
	v_cvt_i32_f32_e32 v11, v11
	v_and_b32_e32 v8, 0xff, v8
	v_and_b32_e32 v9, 0xff, v9
	v_and_b32_e32 v10, 0xff, v10
	v_lshl_or_b32 v8, v9, 8, v8
	v_lshl_or_b32 v8, v10, 16, v8
	v_lshl_or_b32 v135, v11, 24, v8
	v_mul_f32_e32 v8, v41, v72
	v_rndne_f32_e32 v8, v8
	v_cvt_i32_f32_e32 v8, v8
	v_mul_f32_e32 v9, v41, v73
	v_rndne_f32_e32 v9, v9
	v_cvt_i32_f32_e32 v9, v9
	v_mul_f32_e32 v10, v41, v74
	v_rndne_f32_e32 v10, v10
	v_cvt_i32_f32_e32 v10, v10
	v_mul_f32_e32 v11, v41, v75
	v_rndne_f32_e32 v11, v11
	v_cvt_i32_f32_e32 v11, v11
	v_and_b32_e32 v8, 0xff, v8
	v_and_b32_e32 v9, 0xff, v9
	v_and_b32_e32 v10, 0xff, v10
	v_lshl_or_b32 v8, v9, 8, v8
	v_lshl_or_b32 v8, v10, 16, v8
	v_lshl_or_b32 v136, v11, 24, v8
	s_cmp_eq_u32 s25, 0
	s_cbranch_scc1 .Lxp_sxq0
	s_cmp_eq_u32 s25, 1
	s_cbranch_scc1 .Lxp_sxq1
	s_cmp_eq_u32 s25, 2
	s_cbranch_scc1 .Lxp_sxq2
	v_mov_b32_e32 v236, v133
	v_mov_b32_e32 v237, v134
	v_mov_b32_e32 v238, v135
	v_mov_b32_e32 v239, v136
	s_branch .Lxp_sxqd
.Lxp_sxq0:
	v_mov_b32_e32 v224, v133
	v_mov_b32_e32 v225, v134
	v_mov_b32_e32 v226, v135
	v_mov_b32_e32 v227, v136
	s_branch .Lxp_sxqd
.Lxp_sxq1:
	v_mov_b32_e32 v228, v133
	v_mov_b32_e32 v229, v134
	v_mov_b32_e32 v230, v135
	v_mov_b32_e32 v231, v136
	s_branch .Lxp_sxqd
.Lxp_sxq2:
	v_mov_b32_e32 v232, v133
	v_mov_b32_e32 v233, v134
	v_mov_b32_e32 v234, v135
	v_mov_b32_e32 v235, v136
.Lxp_sxqd:
	v_lshl_or_b32 v62, v59, 7, v60
	v_lshlrev_b32_e32 v63, 7, v89
	v_or3_b32 v63, v63, v60, 64
	ds_bpermute_b32 v64, v122, v62
	ds_bpermute_b32 v65, v122, v63
	s_mov_b32 vcc_lo, 0x99999999
	s_mov_b32 vcc_hi, 0x99999999
	s_waitcnt lgkmcnt(0)
	v_min_u32_e32 v66, v62, v64
	v_max_u32_e32 v67, v62, v64
	v_min_u32_e32 v68, v63, v65
	v_max_u32_e32 v69, v63, v65
	v_cndmask_b32_e32 v62, v67, v66, vcc
	v_cndmask_b32_e32 v63, v69, v68, vcc
	ds_bpermute_b32 v64, v123, v62
	ds_bpermute_b32 v65, v123, v63
	s_mov_b32 vcc_lo, 0xc3c3c3c3
	s_mov_b32 vcc_hi, 0xc3c3c3c3
	s_waitcnt lgkmcnt(0)
	v_min_u32_e32 v66, v62, v64
	v_max_u32_e32 v67, v62, v64
	v_min_u32_e32 v68, v63, v65
	v_max_u32_e32 v69, v63, v65
	v_cndmask_b32_e32 v62, v67, v66, vcc
	v_cndmask_b32_e32 v63, v69, v68, vcc
	ds_bpermute_b32 v64, v122, v62
	ds_bpermute_b32 v65, v122, v63
	s_mov_b32 vcc_lo, 0xa5a5a5a5
	s_mov_b32 vcc_hi, 0xa5a5a5a5
	s_waitcnt lgkmcnt(0)
	v_min_u32_e32 v66, v62, v64
	v_max_u32_e32 v67, v62, v64
	v_min_u32_e32 v68, v63, v65
	v_max_u32_e32 v69, v63, v65
	v_cndmask_b32_e32 v62, v67, v66, vcc
	v_cndmask_b32_e32 v63, v69, v68, vcc
	ds_bpermute_b32 v64, v124, v62
	ds_bpermute_b32 v65, v124, v63
	s_mov_b32 vcc_lo, 0xf00ff00f
	s_mov_b32 vcc_hi, 0xf00ff00f
	s_waitcnt lgkmcnt(0)
	v_min_u32_e32 v66, v62, v64
	v_max_u32_e32 v67, v62, v64
	v_min_u32_e32 v68, v63, v65
	v_max_u32_e32 v69, v63, v65
	v_cndmask_b32_e32 v62, v67, v66, vcc
	v_cndmask_b32_e32 v63, v69, v68, vcc
	ds_bpermute_b32 v64, v123, v62
	ds_bpermute_b32 v65, v123, v63
	s_mov_b32 vcc_lo, 0xcc33cc33
	s_mov_b32 vcc_hi, 0xcc33cc33
	s_waitcnt lgkmcnt(0)
	v_min_u32_e32 v66, v62, v64
	v_max_u32_e32 v67, v62, v64
	v_min_u32_e32 v68, v63, v65
	v_max_u32_e32 v69, v63, v65
	v_cndmask_b32_e32 v62, v67, v66, vcc
	v_cndmask_b32_e32 v63, v69, v68, vcc
	ds_bpermute_b32 v64, v122, v62
	ds_bpermute_b32 v65, v122, v63
	s_mov_b32 vcc_lo, 0xaa55aa55
	s_mov_b32 vcc_hi, 0xaa55aa55
	s_waitcnt lgkmcnt(0)
	v_min_u32_e32 v66, v62, v64
	v_max_u32_e32 v67, v62, v64
	v_min_u32_e32 v68, v63, v65
	v_max_u32_e32 v69, v63, v65
	v_cndmask_b32_e32 v62, v67, v66, vcc
	v_cndmask_b32_e32 v63, v69, v68, vcc
	ds_bpermute_b32 v64, v125, v62
	ds_bpermute_b32 v65, v125, v63
	s_mov_b32 vcc_lo, 0xff0000ff
	s_mov_b32 vcc_hi, 0xff0000ff
	s_waitcnt lgkmcnt(0)
	v_min_u32_e32 v66, v62, v64
	v_max_u32_e32 v67, v62, v64
	v_min_u32_e32 v68, v63, v65
	v_max_u32_e32 v69, v63, v65
	v_cndmask_b32_e32 v62, v67, v66, vcc
	v_cndmask_b32_e32 v63, v69, v68, vcc
	ds_bpermute_b32 v64, v124, v62
	ds_bpermute_b32 v65, v124, v63
	s_mov_b32 vcc_lo, 0xf0f00f0f
	s_mov_b32 vcc_hi, 0xf0f00f0f
	s_waitcnt lgkmcnt(0)
	v_min_u32_e32 v66, v62, v64
	v_max_u32_e32 v67, v62, v64
	v_min_u32_e32 v68, v63, v65
	v_max_u32_e32 v69, v63, v65
	v_cndmask_b32_e32 v62, v67, v66, vcc
	v_cndmask_b32_e32 v63, v69, v68, vcc
	ds_bpermute_b32 v64, v123, v62
	ds_bpermute_b32 v65, v123, v63
	s_mov_b32 vcc_lo, 0xcccc3333
	s_mov_b32 vcc_hi, 0xcccc3333
	s_waitcnt lgkmcnt(0)
	v_min_u32_e32 v66, v62, v64
	v_max_u32_e32 v67, v62, v64
	v_min_u32_e32 v68, v63, v65
	v_max_u32_e32 v69, v63, v65
	v_cndmask_b32_e32 v62, v67, v66, vcc
	v_cndmask_b32_e32 v63, v69, v68, vcc
	ds_bpermute_b32 v64, v122, v62
	ds_bpermute_b32 v65, v122, v63
	s_mov_b32 vcc_lo, 0xaaaa5555
	s_mov_b32 vcc_hi, 0xaaaa5555
	s_waitcnt lgkmcnt(0)
	v_min_u32_e32 v66, v62, v64
	v_max_u32_e32 v67, v62, v64
	v_min_u32_e32 v68, v63, v65
	v_max_u32_e32 v69, v63, v65
	v_cndmask_b32_e32 v62, v67, v66, vcc
	v_cndmask_b32_e32 v63, v69, v68, vcc
	ds_bpermute_b32 v64, v126, v62
	ds_bpermute_b32 v65, v126, v63
	s_mov_b32 vcc_lo, 0x0000ffff
	s_mov_b32 vcc_hi, 0xffff0000
	s_waitcnt lgkmcnt(0)
	v_min_u32_e32 v66, v62, v64
	v_max_u32_e32 v67, v62, v64
	v_min_u32_e32 v68, v63, v65
	v_max_u32_e32 v69, v63, v65
	v_cndmask_b32_e32 v62, v67, v66, vcc
	v_cndmask_b32_e32 v63, v69, v68, vcc
	ds_bpermute_b32 v64, v125, v62
	ds_bpermute_b32 v65, v125, v63
	s_mov_b32 vcc_lo, 0x00ff00ff
	s_mov_b32 vcc_hi, 0xff00ff00
	s_waitcnt lgkmcnt(0)
	v_min_u32_e32 v66, v62, v64
	v_max_u32_e32 v67, v62, v64
	v_min_u32_e32 v68, v63, v65
	v_max_u32_e32 v69, v63, v65
	v_cndmask_b32_e32 v62, v67, v66, vcc
	v_cndmask_b32_e32 v63, v69, v68, vcc
	ds_bpermute_b32 v64, v124, v62
	ds_bpermute_b32 v65, v124, v63
	s_mov_b32 vcc_lo, 0x0f0f0f0f
	s_mov_b32 vcc_hi, 0xf0f0f0f0
	s_waitcnt lgkmcnt(0)
	v_min_u32_e32 v66, v62, v64
	v_max_u32_e32 v67, v62, v64
	v_min_u32_e32 v68, v63, v65
	v_max_u32_e32 v69, v63, v65
	v_cndmask_b32_e32 v62, v67, v66, vcc
	v_cndmask_b32_e32 v63, v69, v68, vcc
	ds_bpermute_b32 v64, v123, v62
	ds_bpermute_b32 v65, v123, v63
	s_mov_b32 vcc_lo, 0x33333333
	s_mov_b32 vcc_hi, 0xcccccccc
	s_waitcnt lgkmcnt(0)
	v_min_u32_e32 v66, v62, v64
	v_max_u32_e32 v67, v62, v64
	v_min_u32_e32 v68, v63, v65
	v_max_u32_e32 v69, v63, v65
	v_cndmask_b32_e32 v62, v67, v66, vcc
	v_cndmask_b32_e32 v63, v69, v68, vcc
	ds_bpermute_b32 v64, v122, v62
	ds_bpermute_b32 v65, v122, v63
	s_mov_b32 vcc_lo, 0x55555555
	s_mov_b32 vcc_hi, 0xaaaaaaaa
	s_waitcnt lgkmcnt(0)
	v_min_u32_e32 v66, v62, v64
	v_max_u32_e32 v67, v62, v64
	v_min_u32_e32 v68, v63, v65
	v_max_u32_e32 v69, v63, v65
	v_cndmask_b32_e32 v62, v67, v66, vcc
	v_cndmask_b32_e32 v63, v69, v68, vcc
	ds_bpermute_b32 v64, v127, v62
	ds_bpermute_b32 v65, v127, v63
	s_mov_b32 vcc_lo, 0xffffffff
	s_mov_b32 vcc_hi, 0x00000000
	s_waitcnt lgkmcnt(0)
	v_min_u32_e32 v66, v62, v64
	v_max_u32_e32 v67, v62, v64
	v_min_u32_e32 v68, v63, v65
	v_max_u32_e32 v69, v63, v65
	v_cndmask_b32_e32 v62, v67, v66, vcc
	v_cndmask_b32_e32 v63, v68, v69, vcc
	ds_bpermute_b32 v64, v126, v62
	ds_bpermute_b32 v65, v126, v63
	s_mov_b32 vcc_lo, 0x0000ffff
	s_mov_b32 vcc_hi, 0x0000ffff
	s_waitcnt lgkmcnt(0)
	v_min_u32_e32 v66, v62, v64
	v_max_u32_e32 v67, v62, v64
	v_min_u32_e32 v68, v63, v65
	v_max_u32_e32 v69, v63, v65
	v_cndmask_b32_e32 v62, v67, v66, vcc
	v_cndmask_b32_e32 v63, v68, v69, vcc
	ds_bpermute_b32 v64, v125, v62
	ds_bpermute_b32 v65, v125, v63
	s_mov_b32 vcc_lo, 0x00ff00ff
	s_mov_b32 vcc_hi, 0x00ff00ff
	s_waitcnt lgkmcnt(0)
	v_min_u32_e32 v66, v62, v64
	v_max_u32_e32 v67, v62, v64
	v_min_u32_e32 v68, v63, v65
	v_max_u32_e32 v69, v63, v65
	v_cndmask_b32_e32 v62, v67, v66, vcc
	v_cndmask_b32_e32 v63, v68, v69, vcc
	ds_bpermute_b32 v64, v124, v62
	ds_bpermute_b32 v65, v124, v63
	s_mov_b32 vcc_lo, 0x0f0f0f0f
	s_mov_b32 vcc_hi, 0x0f0f0f0f
	s_waitcnt lgkmcnt(0)
	v_min_u32_e32 v66, v62, v64
	v_max_u32_e32 v67, v62, v64
	v_min_u32_e32 v68, v63, v65
	v_max_u32_e32 v69, v63, v65
	v_cndmask_b32_e32 v62, v67, v66, vcc
	v_cndmask_b32_e32 v63, v68, v69, vcc
	ds_bpermute_b32 v64, v123, v62
	ds_bpermute_b32 v65, v123, v63
	s_mov_b32 vcc_lo, 0x33333333
	s_mov_b32 vcc_hi, 0x33333333
	s_waitcnt lgkmcnt(0)
	v_min_u32_e32 v66, v62, v64
	v_max_u32_e32 v67, v62, v64
	v_min_u32_e32 v68, v63, v65
	v_max_u32_e32 v69, v63, v65
	v_cndmask_b32_e32 v62, v67, v66, vcc
	v_cndmask_b32_e32 v63, v68, v69, vcc
	ds_bpermute_b32 v64, v122, v62
	ds_bpermute_b32 v65, v122, v63
	s_mov_b32 vcc_lo, 0x55555555
	s_mov_b32 vcc_hi, 0x55555555
	s_waitcnt lgkmcnt(0)
	v_min_u32_e32 v66, v62, v64
	v_max_u32_e32 v67, v62, v64
	v_min_u32_e32 v68, v63, v65
	v_max_u32_e32 v69, v63, v65
	v_cndmask_b32_e32 v62, v67, v66, vcc
	v_cndmask_b32_e32 v63, v68, v69, vcc
	v_min_u32_e32 v66, v62, v63
	v_max_u32_e32 v63, v62, v63
	v_mov_b32_e32 v62, v66
	ds_bpermute_b32 v64, v127, v62
	ds_bpermute_b32 v65, v127, v63
	s_mov_b32 vcc_lo, 0xffffffff
	s_mov_b32 vcc_hi, 0x00000000
	s_waitcnt lgkmcnt(0)
	v_min_u32_e32 v66, v62, v64
	v_max_u32_e32 v67, v62, v64
	v_min_u32_e32 v68, v63, v65
	v_max_u32_e32 v69, v63, v65
	v_cndmask_b32_e32 v62, v67, v66, vcc
	v_cndmask_b32_e32 v63, v69, v68, vcc
	ds_bpermute_b32 v64, v126, v62
	ds_bpermute_b32 v65, v126, v63
	s_mov_b32 vcc_lo, 0x0000ffff
	s_mov_b32 vcc_hi, 0x0000ffff
	s_waitcnt lgkmcnt(0)
	v_min_u32_e32 v66, v62, v64
	v_max_u32_e32 v67, v62, v64
	v_min_u32_e32 v68, v63, v65
	v_max_u32_e32 v69, v63, v65
	v_cndmask_b32_e32 v62, v67, v66, vcc
	v_cndmask_b32_e32 v63, v69, v68, vcc
	ds_bpermute_b32 v64, v125, v62
	ds_bpermute_b32 v65, v125, v63
	s_mov_b32 vcc_lo, 0x00ff00ff
	s_mov_b32 vcc_hi, 0x00ff00ff
	s_waitcnt lgkmcnt(0)
	v_min_u32_e32 v66, v62, v64
	v_max_u32_e32 v67, v62, v64
	v_min_u32_e32 v68, v63, v65
	v_max_u32_e32 v69, v63, v65
	v_cndmask_b32_e32 v62, v67, v66, vcc
	v_cndmask_b32_e32 v63, v69, v68, vcc
	ds_bpermute_b32 v64, v124, v62
	ds_bpermute_b32 v65, v124, v63
	s_mov_b32 vcc_lo, 0x0f0f0f0f
	s_mov_b32 vcc_hi, 0x0f0f0f0f
	s_waitcnt lgkmcnt(0)
	v_min_u32_e32 v66, v62, v64
	v_max_u32_e32 v67, v62, v64
	v_min_u32_e32 v68, v63, v65
	v_max_u32_e32 v69, v63, v65
	v_cndmask_b32_e32 v62, v67, v66, vcc
	v_cndmask_b32_e32 v63, v69, v68, vcc
	ds_bpermute_b32 v64, v123, v62
	ds_bpermute_b32 v65, v123, v63
	s_mov_b32 vcc_lo, 0x33333333
	s_mov_b32 vcc_hi, 0x33333333
	s_waitcnt lgkmcnt(0)
	v_min_u32_e32 v66, v62, v64
	v_max_u32_e32 v67, v62, v64
	v_min_u32_e32 v68, v63, v65
	v_max_u32_e32 v69, v63, v65
	v_cndmask_b32_e32 v62, v67, v66, vcc
	v_cndmask_b32_e32 v63, v69, v68, vcc
	ds_bpermute_b32 v64, v122, v62
	ds_bpermute_b32 v65, v122, v63
	s_mov_b32 vcc_lo, 0x55555555
	s_mov_b32 vcc_hi, 0x55555555
	s_waitcnt lgkmcnt(0)
	v_min_u32_e32 v66, v62, v64
	v_max_u32_e32 v67, v62, v64
	v_min_u32_e32 v68, v63, v65
	v_max_u32_e32 v69, v63, v65
	v_cndmask_b32_e32 v62, v67, v66, vcc
	v_cndmask_b32_e32 v63, v69, v68, vcc
	v_lshrrev_b32_e32 v250, 7, v62
	v_lshrrev_b32_e32 v88, 7, v63
	v_and_b32_e32 v64, 63, v62
	v_lshlrev_b32_e32 v64, 2, v64
	v_and_b32_e32 v65, 63, v63
	v_lshlrev_b32_e32 v65, 2, v65
	ds_bpermute_b32 v66, v64, v128
	ds_bpermute_b32 v67, v64, v129
	ds_bpermute_b32 v68, v65, v128
	ds_bpermute_b32 v69, v65, v129
	v_and_b32_e32 v70, 64, v62
	v_and_b32_e32 v71, 64, v63
	s_waitcnt lgkmcnt(0)
	v_cmp_eq_u32_e32 vcc, 0, v70
	s_nop 1
	v_cndmask_b32_e32 v251, v67, v66, vcc
	v_cmp_eq_u32_e32 vcc, 0, v71
	s_nop 1
	v_cndmask_b32_e32 v89, v69, v68, vcc
	s_add_i32 s2, s32, s25
	s_lshl_b32 s2, s2, 11
	v_lshl_add_u32 v249, v60, 3, s2
	global_store_dwordx2 v249, v[250:251], s[92:93]
	global_store_dwordx2 v249, v[88:89], s[92:93] offset:512
	v_and_b32_e32 v252, 15, v60
	v_lshlrev_b32_e32 v252, 4, v252
	ds_bpermute_b32 v64, v252, v250
	ds_bpermute_b32 v65, v252, v88
	s_mov_b32 vcc_lo, 0xffff0000
	s_mov_b32 vcc_hi, 0xffff0000
	s_waitcnt lgkmcnt(0)
	v_cndmask_b32_e32 v64, v64, v65, vcc
	v_and_b32_e32 v65, 31, v60
	s_lshl_b32 s2, s25, 5
	v_or_b32_e32 v65, s2, v65
	v_lshl_or_b32 v64, v64, 7, v65
	s_cmp_eq_u32 s25, 0
	s_cbranch_scc1 .Lxp_uk0
	s_cmp_eq_u32 s25, 1
	s_cbranch_scc1 .Lxp_uk1
	s_cmp_eq_u32 s25, 2
	s_cbranch_scc1 .Lxp_uk2
	s_mov_b32 vcc_lo, 0
	s_mov_b32 vcc_hi, -1
	s_nop 0
	v_cndmask_b32_e32 v241, v241, v64, vcc
	s_branch .Lxp_ukd
.Lxp_uk0:
	s_mov_b32 vcc_lo, -1
	s_mov_b32 vcc_hi, 0
	s_nop 0
	v_cndmask_b32_e32 v240, v240, v64, vcc
	s_branch .Lxp_ukd
.Lxp_uk1:
	s_mov_b32 vcc_lo, 0
	s_mov_b32 vcc_hi, -1
	s_nop 0
	v_cndmask_b32_e32 v240, v240, v64, vcc
	s_branch .Lxp_ukd
.Lxp_uk2:
	s_mov_b32 vcc_lo, -1
	s_mov_b32 vcc_hi, 0
	s_nop 0
	v_cndmask_b32_e32 v241, v241, v64, vcc
.Lxp_ukd:
	s_add_i32 s25, s25, 1
	s_cmp_lt_u32 s25, 4
	s_cbranch_scc1 .Lxp_tok
	s_waitcnt vmcnt(0)
	global_load_dword v70, v[246:247], off sc1
	ds_bpermute_b32 v64, v122, v240
	ds_bpermute_b32 v65, v122, v241
	s_mov_b32 vcc_lo, 0x99999999
	s_mov_b32 vcc_hi, 0x99999999
	s_waitcnt lgkmcnt(0)
	v_min_u32_e32 v66, v240, v64
	v_max_u32_e32 v67, v240, v64
	v_min_u32_e32 v68, v241, v65
	v_max_u32_e32 v69, v241, v65
	v_cndmask_b32_e32 v240, v67, v66, vcc
	v_cndmask_b32_e32 v241, v69, v68, vcc
	ds_bpermute_b32 v64, v123, v240
	ds_bpermute_b32 v65, v123, v241
	s_mov_b32 vcc_lo, 0xc3c3c3c3
	s_mov_b32 vcc_hi, 0xc3c3c3c3
	s_waitcnt lgkmcnt(0)
	v_min_u32_e32 v66, v240, v64
	v_max_u32_e32 v67, v240, v64
	v_min_u32_e32 v68, v241, v65
	v_max_u32_e32 v69, v241, v65
	v_cndmask_b32_e32 v240, v67, v66, vcc
	v_cndmask_b32_e32 v241, v69, v68, vcc
	ds_bpermute_b32 v64, v122, v240
	ds_bpermute_b32 v65, v122, v241
	s_mov_b32 vcc_lo, 0xa5a5a5a5
	s_mov_b32 vcc_hi, 0xa5a5a5a5
	s_waitcnt lgkmcnt(0)
	v_min_u32_e32 v66, v240, v64
	v_max_u32_e32 v67, v240, v64
	v_min_u32_e32 v68, v241, v65
	v_max_u32_e32 v69, v241, v65
	v_cndmask_b32_e32 v240, v67, v66, vcc
	v_cndmask_b32_e32 v241, v69, v68, vcc
	ds_bpermute_b32 v64, v124, v240
	ds_bpermute_b32 v65, v124, v241
	s_mov_b32 vcc_lo, 0xf00ff00f
	s_mov_b32 vcc_hi, 0xf00ff00f
	s_waitcnt lgkmcnt(0)
	v_min_u32_e32 v66, v240, v64
	v_max_u32_e32 v67, v240, v64
	v_min_u32_e32 v68, v241, v65
	v_max_u32_e32 v69, v241, v65
	v_cndmask_b32_e32 v240, v67, v66, vcc
	v_cndmask_b32_e32 v241, v69, v68, vcc
	ds_bpermute_b32 v64, v123, v240
	ds_bpermute_b32 v65, v123, v241
	s_mov_b32 vcc_lo, 0xcc33cc33
	s_mov_b32 vcc_hi, 0xcc33cc33
	s_waitcnt lgkmcnt(0)
	v_min_u32_e32 v66, v240, v64
	v_max_u32_e32 v67, v240, v64
	v_min_u32_e32 v68, v241, v65
	v_max_u32_e32 v69, v241, v65
	v_cndmask_b32_e32 v240, v67, v66, vcc
	v_cndmask_b32_e32 v241, v69, v68, vcc
	ds_bpermute_b32 v64, v122, v240
	ds_bpermute_b32 v65, v122, v241
	s_mov_b32 vcc_lo, 0xaa55aa55
	s_mov_b32 vcc_hi, 0xaa55aa55
	s_waitcnt lgkmcnt(0)
	v_min_u32_e32 v66, v240, v64
	v_max_u32_e32 v67, v240, v64
	v_min_u32_e32 v68, v241, v65
	v_max_u32_e32 v69, v241, v65
	v_cndmask_b32_e32 v240, v67, v66, vcc
	v_cndmask_b32_e32 v241, v69, v68, vcc
	ds_bpermute_b32 v64, v125, v240
	ds_bpermute_b32 v65, v125, v241
	s_mov_b32 vcc_lo, 0xff0000ff
	s_mov_b32 vcc_hi, 0xff0000ff
	s_waitcnt lgkmcnt(0)
	v_min_u32_e32 v66, v240, v64
	v_max_u32_e32 v67, v240, v64
	v_min_u32_e32 v68, v241, v65
	v_max_u32_e32 v69, v241, v65
	v_cndmask_b32_e32 v240, v67, v66, vcc
	v_cndmask_b32_e32 v241, v69, v68, vcc
	ds_bpermute_b32 v64, v124, v240
	ds_bpermute_b32 v65, v124, v241
	s_mov_b32 vcc_lo, 0xf0f00f0f
	s_mov_b32 vcc_hi, 0xf0f00f0f
	s_waitcnt lgkmcnt(0)
	v_min_u32_e32 v66, v240, v64
	v_max_u32_e32 v67, v240, v64
	v_min_u32_e32 v68, v241, v65
	v_max_u32_e32 v69, v241, v65
	v_cndmask_b32_e32 v240, v67, v66, vcc
	v_cndmask_b32_e32 v241, v69, v68, vcc
	ds_bpermute_b32 v64, v123, v240
	ds_bpermute_b32 v65, v123, v241
	s_mov_b32 vcc_lo, 0xcccc3333
	s_mov_b32 vcc_hi, 0xcccc3333
	s_waitcnt lgkmcnt(0)
	v_min_u32_e32 v66, v240, v64
	v_max_u32_e32 v67, v240, v64
	v_min_u32_e32 v68, v241, v65
	v_max_u32_e32 v69, v241, v65
	v_cndmask_b32_e32 v240, v67, v66, vcc
	v_cndmask_b32_e32 v241, v69, v68, vcc
	ds_bpermute_b32 v64, v122, v240
	ds_bpermute_b32 v65, v122, v241
	s_mov_b32 vcc_lo, 0xaaaa5555
	s_mov_b32 vcc_hi, 0xaaaa5555
	s_waitcnt lgkmcnt(0)
	v_min_u32_e32 v66, v240, v64
	v_max_u32_e32 v67, v240, v64
	v_min_u32_e32 v68, v241, v65
	v_max_u32_e32 v69, v241, v65
	v_cndmask_b32_e32 v240, v67, v66, vcc
	v_cndmask_b32_e32 v241, v69, v68, vcc
	ds_bpermute_b32 v64, v126, v240
	ds_bpermute_b32 v65, v126, v241
	s_mov_b32 vcc_lo, 0x0000ffff
	s_mov_b32 vcc_hi, 0xffff0000
	s_waitcnt lgkmcnt(0)
	v_min_u32_e32 v66, v240, v64
	v_max_u32_e32 v67, v240, v64
	v_min_u32_e32 v68, v241, v65
	v_max_u32_e32 v69, v241, v65
	v_cndmask_b32_e32 v240, v67, v66, vcc
	v_cndmask_b32_e32 v241, v69, v68, vcc
	ds_bpermute_b32 v64, v125, v240
	ds_bpermute_b32 v65, v125, v241
	s_mov_b32 vcc_lo, 0x00ff00ff
	s_mov_b32 vcc_hi, 0xff00ff00
	s_waitcnt lgkmcnt(0)
	v_min_u32_e32 v66, v240, v64
	v_max_u32_e32 v67, v240, v64
	v_min_u32_e32 v68, v241, v65
	v_max_u32_e32 v69, v241, v65
	v_cndmask_b32_e32 v240, v67, v66, vcc
	v_cndmask_b32_e32 v241, v69, v68, vcc
	ds_bpermute_b32 v64, v124, v240
	ds_bpermute_b32 v65, v124, v241
	s_mov_b32 vcc_lo, 0x0f0f0f0f
	s_mov_b32 vcc_hi, 0xf0f0f0f0
	s_waitcnt lgkmcnt(0)
	v_min_u32_e32 v66, v240, v64
	v_max_u32_e32 v67, v240, v64
	v_min_u32_e32 v68, v241, v65
	v_max_u32_e32 v69, v241, v65
	v_cndmask_b32_e32 v240, v67, v66, vcc
	v_cndmask_b32_e32 v241, v69, v68, vcc
	ds_bpermute_b32 v64, v123, v240
	ds_bpermute_b32 v65, v123, v241
	s_mov_b32 vcc_lo, 0x33333333
	s_mov_b32 vcc_hi, 0xcccccccc
	s_waitcnt lgkmcnt(0)
	v_min_u32_e32 v66, v240, v64
	v_max_u32_e32 v67, v240, v64
	v_min_u32_e32 v68, v241, v65
	v_max_u32_e32 v69, v241, v65
	v_cndmask_b32_e32 v240, v67, v66, vcc
	v_cndmask_b32_e32 v241, v69, v68, vcc
	ds_bpermute_b32 v64, v122, v240
	ds_bpermute_b32 v65, v122, v241
	s_mov_b32 vcc_lo, 0x55555555
	s_mov_b32 vcc_hi, 0xaaaaaaaa
	s_waitcnt lgkmcnt(0)
	v_min_u32_e32 v66, v240, v64
	v_max_u32_e32 v67, v240, v64
	v_min_u32_e32 v68, v241, v65
	v_max_u32_e32 v69, v241, v65
	v_cndmask_b32_e32 v240, v67, v66, vcc
	v_cndmask_b32_e32 v241, v69, v68, vcc
	ds_bpermute_b32 v64, v127, v240
	ds_bpermute_b32 v65, v127, v241
	s_mov_b32 vcc_lo, 0xffffffff
	s_mov_b32 vcc_hi, 0x00000000
	s_waitcnt lgkmcnt(0)
	v_min_u32_e32 v66, v240, v64
	v_max_u32_e32 v67, v240, v64
	v_min_u32_e32 v68, v241, v65
	v_max_u32_e32 v69, v241, v65
	v_cndmask_b32_e32 v240, v67, v66, vcc
	v_cndmask_b32_e32 v241, v68, v69, vcc
	ds_bpermute_b32 v64, v126, v240
	ds_bpermute_b32 v65, v126, v241
	s_mov_b32 vcc_lo, 0x0000ffff
	s_mov_b32 vcc_hi, 0x0000ffff
	s_waitcnt lgkmcnt(0)
	v_min_u32_e32 v66, v240, v64
	v_max_u32_e32 v67, v240, v64
	v_min_u32_e32 v68, v241, v65
	v_max_u32_e32 v69, v241, v65
	v_cndmask_b32_e32 v240, v67, v66, vcc
	v_cndmask_b32_e32 v241, v68, v69, vcc
	ds_bpermute_b32 v64, v125, v240
	ds_bpermute_b32 v65, v125, v241
	s_mov_b32 vcc_lo, 0x00ff00ff
	s_mov_b32 vcc_hi, 0x00ff00ff
	s_waitcnt lgkmcnt(0)
	v_min_u32_e32 v66, v240, v64
	v_max_u32_e32 v67, v240, v64
	v_min_u32_e32 v68, v241, v65
	v_max_u32_e32 v69, v241, v65
	v_cndmask_b32_e32 v240, v67, v66, vcc
	v_cndmask_b32_e32 v241, v68, v69, vcc
	ds_bpermute_b32 v64, v124, v240
	ds_bpermute_b32 v65, v124, v241
	s_mov_b32 vcc_lo, 0x0f0f0f0f
	s_mov_b32 vcc_hi, 0x0f0f0f0f
	s_waitcnt lgkmcnt(0)
	v_min_u32_e32 v66, v240, v64
	v_max_u32_e32 v67, v240, v64
	v_min_u32_e32 v68, v241, v65
	v_max_u32_e32 v69, v241, v65
	v_cndmask_b32_e32 v240, v67, v66, vcc
	v_cndmask_b32_e32 v241, v68, v69, vcc
	ds_bpermute_b32 v64, v123, v240
	ds_bpermute_b32 v65, v123, v241
	s_mov_b32 vcc_lo, 0x33333333
	s_mov_b32 vcc_hi, 0x33333333
	s_waitcnt lgkmcnt(0)
	v_min_u32_e32 v66, v240, v64
	v_max_u32_e32 v67, v240, v64
	v_min_u32_e32 v68, v241, v65
	v_max_u32_e32 v69, v241, v65
	v_cndmask_b32_e32 v240, v67, v66, vcc
	v_cndmask_b32_e32 v241, v68, v69, vcc
	ds_bpermute_b32 v64, v122, v240
	ds_bpermute_b32 v65, v122, v241
	s_mov_b32 vcc_lo, 0x55555555
	s_mov_b32 vcc_hi, 0x55555555
	s_waitcnt lgkmcnt(0)
	v_min_u32_e32 v66, v240, v64
	v_max_u32_e32 v67, v240, v64
	v_min_u32_e32 v68, v241, v65
	v_max_u32_e32 v69, v241, v65
	v_cndmask_b32_e32 v240, v67, v66, vcc
	v_cndmask_b32_e32 v241, v68, v69, vcc
	v_min_u32_e32 v66, v240, v241
	v_max_u32_e32 v241, v240, v241
	v_mov_b32_e32 v240, v66
	ds_bpermute_b32 v64, v127, v240
	ds_bpermute_b32 v65, v127, v241
	s_mov_b32 vcc_lo, 0xffffffff
	s_mov_b32 vcc_hi, 0x00000000
	s_waitcnt lgkmcnt(0)
	v_min_u32_e32 v66, v240, v64
	v_max_u32_e32 v67, v240, v64
	v_min_u32_e32 v68, v241, v65
	v_max_u32_e32 v69, v241, v65
	v_cndmask_b32_e32 v240, v67, v66, vcc
	v_cndmask_b32_e32 v241, v69, v68, vcc
	ds_bpermute_b32 v64, v126, v240
	ds_bpermute_b32 v65, v126, v241
	s_mov_b32 vcc_lo, 0x0000ffff
	s_mov_b32 vcc_hi, 0x0000ffff
	s_waitcnt lgkmcnt(0)
	v_min_u32_e32 v66, v240, v64
	v_max_u32_e32 v67, v240, v64
	v_min_u32_e32 v68, v241, v65
	v_max_u32_e32 v69, v241, v65
	v_cndmask_b32_e32 v240, v67, v66, vcc
	v_cndmask_b32_e32 v241, v69, v68, vcc
	ds_bpermute_b32 v64, v125, v240
	ds_bpermute_b32 v65, v125, v241
	s_mov_b32 vcc_lo, 0x00ff00ff
	s_mov_b32 vcc_hi, 0x00ff00ff
	s_waitcnt lgkmcnt(0)
	v_min_u32_e32 v66, v240, v64
	v_max_u32_e32 v67, v240, v64
	v_min_u32_e32 v68, v241, v65
	v_max_u32_e32 v69, v241, v65
	v_cndmask_b32_e32 v240, v67, v66, vcc
	v_cndmask_b32_e32 v241, v69, v68, vcc
	ds_bpermute_b32 v64, v124, v240
	ds_bpermute_b32 v65, v124, v241
	s_mov_b32 vcc_lo, 0x0f0f0f0f
	s_mov_b32 vcc_hi, 0x0f0f0f0f
	s_waitcnt lgkmcnt(0)
	v_min_u32_e32 v66, v240, v64
	v_max_u32_e32 v67, v240, v64
	v_min_u32_e32 v68, v241, v65
	v_max_u32_e32 v69, v241, v65
	v_cndmask_b32_e32 v240, v67, v66, vcc
	v_cndmask_b32_e32 v241, v69, v68, vcc
	ds_bpermute_b32 v64, v123, v240
	ds_bpermute_b32 v65, v123, v241
	s_mov_b32 vcc_lo, 0x33333333
	s_mov_b32 vcc_hi, 0x33333333
	s_waitcnt lgkmcnt(0)
	v_min_u32_e32 v66, v240, v64
	v_max_u32_e32 v67, v240, v64
	v_min_u32_e32 v68, v241, v65
	v_max_u32_e32 v69, v241, v65
	v_cndmask_b32_e32 v240, v67, v66, vcc
	v_cndmask_b32_e32 v241, v69, v68, vcc
	ds_bpermute_b32 v64, v122, v240
	ds_bpermute_b32 v65, v122, v241
	s_mov_b32 vcc_lo, 0x55555555
	s_mov_b32 vcc_hi, 0x55555555
	s_waitcnt lgkmcnt(0)
	v_min_u32_e32 v66, v240, v64
	v_max_u32_e32 v67, v240, v64
	v_min_u32_e32 v68, v241, v65
	v_max_u32_e32 v69, v241, v65
	v_cndmask_b32_e32 v240, v67, v66, vcc
	v_cndmask_b32_e32 v241, v69, v68, vcc
	s_waitcnt vmcnt(0)
	v_readfirstlane_b32 s2, v70
	s_and_b32 s2, s2, 0x3fff
	s_mov_b32 s97, s2
	s_lshl_b32 s3, s2, 7
	v_cmp_gt_u32_e32 vcc, s3, v240
	s_nop 1
	s_bcnt1_i32_b64 s2, vcc
	v_cmp_gt_u32_e32 vcc, s3, v241
	s_nop 1
	s_bcnt1_i32_b64 s3, vcc
	s_add_i32 s2, s2, s3
	v_add_u32_e32 v64, s2, v60
	v_and_b32_e32 v64, 0x7f, v64
	v_and_b32_e32 v65, 63, v64
	v_lshlrev_b32_e32 v65, 2, v65
	ds_bpermute_b32 v66, v65, v240
	ds_bpermute_b32 v67, v65, v241
	v_cmp_gt_u32_e32 vcc, 64, v64
	s_waitcnt lgkmcnt(0)
	v_cndmask_b32_e32 v240, v67, v66, vcc
	v_cndmask_b32_e32 v241, v66, v67, vcc
	s_nop 1
	v_readlane_b32 s2, v240, 0
	s_and_b32 s3, s2, 31
	s_lshl_b32 s3, s3, 5
	s_bfe_u32 s94, s2, 0x20005
	s_lshl_b32 s2, s94, 11
	s_add_i32 s3, s3, s2
	s_load_dwordx8 s[84:91], s[36:37], s3
	s_waitcnt lgkmcnt(0)
	s_and_b32 s84, s84, 0x3fff
	s_lshl_b32 s2, s84, 11
	v_lshl_add_u32 v249, v60, 4, s2
	global_load_dwordx4 v[8:11], v249, s[18:19]
	global_load_dwordx4 v[40:43], v249, s[20:21]
	s_lshl_b32 s2, s84, 2
	v_writelane_b32 v147, s2, 0
	s_and_b32 s86, s86, 0x3fff
	s_lshl_b32 s2, s86, 11
	v_lshl_add_u32 v249, v60, 4, s2
	global_load_dwordx4 v[16:19], v249, s[18:19]
	global_load_dwordx4 v[44:47], v249, s[20:21]
	s_lshl_b32 s2, s86, 2
	v_writelane_b32 v147, s2, 1
	s_and_b32 s88, s88, 0x3fff
	s_lshl_b32 s2, s88, 11
	v_lshl_add_u32 v249, v60, 4, s2
	global_load_dwordx4 v[32:35], v249, s[18:19]
	global_load_dwordx4 v[48:51], v249, s[20:21]
	s_lshl_b32 s2, s88, 2
	v_writelane_b32 v147, s2, 2
	s_and_b32 s90, s90, 0x3fff
	s_lshl_b32 s2, s90, 11
	v_lshl_add_u32 v249, v60, 4, s2
	global_load_dwordx4 v[36:39], v249, s[18:19]
	global_load_dwordx4 v[52:55], v249, s[20:21]
	s_lshl_b32 s2, s90, 2
	v_writelane_b32 v147, s2, 3
	global_load_dword v138, v147, s[44:45]
	global_load_dword v139, v147, s[46:47]
	s_mov_b32 s8, s85
	s_mov_b32 s9, s87
	s_mov_b32 s10, s89
	s_mov_b32 s11, s91
	s_mov_b32 s33, s94
	v_readlane_b32 s2, v240, 1
	s_and_b32 s3, s2, 31
	s_lshl_b32 s3, s3, 5
	s_bfe_u32 s94, s2, 0x20005
	s_lshl_b32 s2, s94, 11
	s_add_i32 s3, s3, s2
	s_load_dwordx8 s[84:91], s[36:37], s3
	s_waitcnt vmcnt(0)
	v_mov_b64_e32 v[152:153], v[8:9]
	v_mov_b64_e32 v[154:155], v[10:11]
	v_mov_b64_e32 v[156:157], v[16:17]
	v_mov_b64_e32 v[158:159], v[18:19]
	v_mov_b64_e32 v[160:161], v[32:33]
	v_mov_b64_e32 v[162:163], v[34:35]
	v_mov_b64_e32 v[164:165], v[36:37]
	v_mov_b64_e32 v[166:167], v[38:39]
	v_mov_b64_e32 v[12:13], v[40:41]
	v_mov_b64_e32 v[14:15], v[42:43]
	v_mov_b64_e32 v[20:21], v[44:45]
	v_mov_b64_e32 v[22:23], v[46:47]
	v_mov_b64_e32 v[24:25], v[48:49]
	v_mov_b64_e32 v[26:27], v[50:51]
	v_mov_b64_e32 v[28:29], v[52:53]
	v_mov_b64_e32 v[30:31], v[54:55]
	v_mov_b32_e32 v140, v138
	v_mov_b32_e32 v141, v139
	v_mov_b32_e32 v90, 0
	v_mov_b32_e32 v91, 0
	v_mov_b32_e32 v92, 0
	v_mov_b32_e32 v93, 0
	v_mov_b32_e32 v94, 0
	v_mov_b32_e32 v95, 0
	v_mov_b32_e32 v96, 0
	v_mov_b32_e32 v97, 0
	v_mov_b32_e32 v98, 0
	v_mov_b32_e32 v99, 0
	v_mov_b32_e32 v100, 0
	v_mov_b32_e32 v101, 0
	v_mov_b32_e32 v102, 0
	v_mov_b32_e32 v103, 0
	v_mov_b32_e32 v104, 0
	v_mov_b32_e32 v105, 0
	v_mov_b32_e32 v142, 0
	v_readlane_b32 s3, v244, s33
	s_nop 1
	v_mov_b32_e32 v137, s3
	s_cmp_eq_u32 s33, 0
	s_cbranch_scc1 .Lxp_ixq0
	s_cmp_eq_u32 s33, 1
	s_cbranch_scc1 .Lxp_ixq1
	s_cmp_eq_u32 s33, 2
	s_cbranch_scc1 .Lxp_ixq2
	v_mov_b32_e32 v133, v236
	v_mov_b32_e32 v134, v237
	v_mov_b32_e32 v135, v238
	v_mov_b32_e32 v136, v239
	s_branch .Lxp_ixqd
.Lxp_ixq0:
	v_mov_b32_e32 v133, v224
	v_mov_b32_e32 v134, v225
	v_mov_b32_e32 v135, v226
	v_mov_b32_e32 v136, v227
	s_branch .Lxp_ixqd
.Lxp_ixq1:
	v_mov_b32_e32 v133, v228
	v_mov_b32_e32 v134, v229
	v_mov_b32_e32 v135, v230
	v_mov_b32_e32 v136, v231
	s_branch .Lxp_ixqd
.Lxp_ixq2:
	v_mov_b32_e32 v133, v232
	v_mov_b32_e32 v134, v233
	v_mov_b32_e32 v135, v234
	v_mov_b32_e32 v136, v235
.Lxp_ixqd:
	s_mov_b32 s25, 0
.Lxp_unit:
	s_cmp_lt_u32 s96, 8
	s_cbranch_scc0 .Lxp_nopub
	v_cmp_eq_u32_e32 vcc, 0, v58
	s_lshl_b32 s2, s25, 7
	s_add_i32 s2, s2, s97
	s_and_b32 s2, s2, 0x3fff
	v_mov_b32_e32 v245, s2
	s_and_b64 exec, vcc, 1
	global_store_dword v[246:247], v245, off
	s_mov_b64 exec, -1
.Lxp_nopub:
	s_waitcnt lgkmcnt(0)
	s_and_b32 s84, s84, 0x3fff
	s_lshl_b32 s2, s84, 11
	v_lshl_add_u32 v249, v60, 4, s2
	global_load_dwordx4 v[8:11], v249, s[18:19]
	global_load_dwordx4 v[40:43], v249, s[20:21]
	s_lshl_b32 s2, s84, 2
	v_writelane_b32 v147, s2, 0
	s_and_b32 s86, s86, 0x3fff
	s_lshl_b32 s2, s86, 11
	v_lshl_add_u32 v249, v60, 4, s2
	global_load_dwordx4 v[16:19], v249, s[18:19]
	global_load_dwordx4 v[44:47], v249, s[20:21]
	s_lshl_b32 s2, s86, 2
	v_writelane_b32 v147, s2, 1
	s_and_b32 s88, s88, 0x3fff
	s_lshl_b32 s2, s88, 11
	v_lshl_add_u32 v249, v60, 4, s2
	global_load_dwordx4 v[32:35], v249, s[18:19]
	global_load_dwordx4 v[48:51], v249, s[20:21]
	s_lshl_b32 s2, s88, 2
	v_writelane_b32 v147, s2, 2
	s_and_b32 s90, s90, 0x3fff
	s_lshl_b32 s2, s90, 11
	v_lshl_add_u32 v249, v60, 4, s2
	global_load_dwordx4 v[36:39], v249, s[18:19]
	global_load_dwordx4 v[52:55], v249, s[20:21]
	s_lshl_b32 s2, s90, 2
	v_writelane_b32 v147, s2, 3
	global_load_dword v138, v147, s[44:45]
	global_load_dword v139, v147, s[46:47]
	s_mov_b32 s76, s85
	s_mov_b32 s77, s87
	s_mov_b32 s78, s89
	s_mov_b32 s79, s91
	s_mov_b32 s80, s94
	s_add_i32 s3, s25, 2
	s_min_u32 s3, s3, 0x7f
	s_cmp_lt_u32 s3, 64
	s_cselect_b64 vcc, -1, 0
	s_nop 0
	v_cndmask_b32_e32 v249, v241, v240, vcc
	s_nop 1
	v_readlane_b32 s2, v249, s3
	s_and_b32 s3, s2, 31
	s_lshl_b32 s3, s3, 5
	s_bfe_u32 s94, s2, 0x20005
	s_lshl_b32 s2, s94, 11
	s_add_i32 s3, s3, s2
	s_load_dwordx8 s[84:91], s[36:37], s3
	v_mov_b32_e32 v171, 0
	v_mov_b32_e32 v149, 0
	v_mov_b32_e32 v150, 0
	v_mov_b32_e32 v151, 0
	v_dot4c_i32_i8_e32 v171, v152, v133
	v_dot4c_i32_i8_e32 v149, v156, v133
	v_dot4c_i32_i8_e32 v150, v160, v133
	v_dot4c_i32_i8_e32 v151, v164, v133
	v_dot4c_i32_i8_e32 v171, v153, v134
	v_dot4c_i32_i8_e32 v149, v157, v134
	v_dot4c_i32_i8_e32 v150, v161, v134
	v_dot4c_i32_i8_e32 v151, v165, v134
	v_dot4c_i32_i8_e32 v171, v154, v135
	v_dot4c_i32_i8_e32 v149, v158, v135
	v_dot4c_i32_i8_e32 v150, v162, v135
	v_dot4c_i32_i8_e32 v151, v166, v135
	v_dot4c_i32_i8_e32 v171, v155, v136
	v_dot4c_i32_i8_e32 v149, v159, v136
	v_dot4c_i32_i8_e32 v150, v163, v136
	v_dot4c_i32_i8_e32 v151, v167, v136
	s_nop 3
	v_cndmask_b32_e64 v143, v171, v149, s[0:1]
	v_cndmask_b32_e64 v144, v149, v171, s[0:1]
	v_cndmask_b32_e64 v145, v150, v151, s[0:1]
	v_cndmask_b32_e64 v146, v151, v150, s[0:1]
	s_nop 1
	v_add_u32_dpp v144, v143, v144 quad_perm:[1,0,3,2] row_mask:0xf bank_mask:0xf
	v_add_u32_dpp v146, v145, v146 quad_perm:[1,0,3,2] row_mask:0xf bank_mask:0xf
	s_nop 1
	v_cndmask_b32_e64 v143, v144, v146, s[6:7]
	v_cndmask_b32_e64 v145, v146, v144, s[6:7]
	s_nop 1
	v_add_u32_dpp v145, v143, v145 quad_perm:[2,3,0,1] row_mask:0xf bank_mask:0xf
	s_nop 1
	v_add_u32_dpp v145, v145, v145 row_ror:4 row_mask:0xf bank_mask:0xf
	s_nop 1
	v_add_u32_dpp v145, v145, v145 row_ror:8 row_mask:0xf bank_mask:0xf
	s_nop 1
	ds_bpermute_b32 v143, v126, v145
	s_waitcnt lgkmcnt(0)
	v_add_u32_e32 v145, v145, v143
	ds_bpermute_b32 v143, v127, v145
	s_waitcnt lgkmcnt(0)
	v_add_u32_e32 v145, v145, v143
	v_cvt_f32_i32_e32 v152, v145
	v_mul_f32_e32 v151, v140, v152
	v_mul_f32_e32 v151, v137, v151
	v_mul_f32_e32 v152, 0x3f3504f3, v151
	v_fma_f32 v153, |v152|, s66, v120
	v_fma_f32 v153, |v152|, v153, s67
	v_fma_f32 v153, |v152|, v153, s68
	v_fma_f32 v153, |v152|, v153, s69
	v_fma_f32 v153, |v152|, v153, s70
	v_fma_f32 v153, |v152|, v153, s71
	v_fma_f32 v153, |v152|, v153, |v152|
	v_mul_f32_e32 v154, 0xbfb8aa3b, v153
	v_fma_f32 v155, v153, s72, -v154
	v_rndne_f32_e32 v156, v154
	v_fmac_f32_e32 v155, 0xb2a5705f, v153
	v_sub_f32_e32 v154, v154, v156
	v_add_f32_e32 v154, v154, v155
	v_cvt_i32_f32_e32 v155, v156
	v_exp_f32_e32 v154, v154
	v_cmp_nlt_f32_e32 vcc, s73, v153
	v_ldexp_f32 v154, v154, v155
	s_nop 0
	v_cndmask_b32_e32 v154, 0, v154, vcc
	v_cmp_ngt_f32_e32 vcc, s74, v153
	s_nop 1
	v_cndmask_b32_e32 v153, v121, v154, vcc
	v_sub_f32_e32 v153, 1.0, v153
	v_mul_f32_e32 v168, v152, v152
	v_fmamk_f32 v169, v168, 0xba1345e1, v117
	v_fmaak_f32 v169, v168, v169, 0xbcdac9b8
	v_fmaak_f32 v169, v168, v169, 0x3de703be
	v_fmaak_f32 v169, v168, v169, 0xbec09330
	v_fmaak_f32 v168, v168, v169, 0x3e0375d0
	v_fma_f32 v168, |v152|, v168, |v152|
	v_cmp_nlt_f32_e64 vcc, |v152|, 1.0
	s_nop 1
	v_cndmask_b32_e32 v153, v168, v153, vcc
	v_bfi_b32 v146, s75, v153, v152
	v_mul_f32_e32 v145, 0.5, v151
	v_add_f32_e32 v146, 1.0, v146
	v_mul_f32_e32 v145, v145, v146
	v_writelane_b32 v148, s8, 0
	v_writelane_b32 v148, s9, 1
	v_writelane_b32 v148, s10, 2
	v_writelane_b32 v148, s11, 3
	v_mul_f32_e32 v144, v148, v145
	v_mul_f32_e32 v143, v141, v144
	s_nop 1
	v_readlane_b32 s40, v143, 0
	v_readlane_b32 s38, v143, 1
	v_readlane_b32 s42, v143, 2
	v_readlane_b32 s2, v143, 3
	s_nop 1
	v_add_f32_e32 v142, s40, v142
	v_add_f32_e32 v142, s38, v142
	v_add_f32_e32 v142, s42, v142
	v_add_f32_e32 v142, s2, v142
	v_cvt_f32_ubyte1_e32 v169, v12
	v_cvt_f32_ubyte0_e32 v168, v12
	v_pk_fma_f32 v[104:105], s[40:41], v[168:169], v[104:105] op_sel_hi:[0,1,1]
	v_cvt_f32_ubyte1_e32 v171, v20
	v_cvt_f32_ubyte0_e32 v170, v20
	v_pk_fma_f32 v[104:105], s[38:39], v[170:171], v[104:105] op_sel_hi:[0,1,1]
	v_cvt_f32_ubyte1_e32 v169, v24
	v_cvt_f32_ubyte0_e32 v168, v24
	v_pk_fma_f32 v[104:105], s[42:43], v[168:169], v[104:105] op_sel_hi:[0,1,1]
	v_cvt_f32_ubyte1_e32 v171, v28
	v_cvt_f32_ubyte0_e32 v170, v28
	v_pk_fma_f32 v[104:105], s[2:3], v[170:171], v[104:105] op_sel_hi:[0,1,1]
	v_cvt_f32_ubyte3_e32 v169, v12
	v_cvt_f32_ubyte2_e32 v168, v12
	v_pk_fma_f32 v[102:103], s[40:41], v[168:169], v[102:103] op_sel_hi:[0,1,1]
	v_cvt_f32_ubyte3_e32 v171, v20
	v_cvt_f32_ubyte2_e32 v170, v20
	v_pk_fma_f32 v[102:103], s[38:39], v[170:171], v[102:103] op_sel_hi:[0,1,1]
	v_cvt_f32_ubyte3_e32 v169, v24
	v_cvt_f32_ubyte2_e32 v168, v24
	v_pk_fma_f32 v[102:103], s[42:43], v[168:169], v[102:103] op_sel_hi:[0,1,1]
	v_cvt_f32_ubyte3_e32 v171, v28
	v_cvt_f32_ubyte2_e32 v170, v28
	v_pk_fma_f32 v[102:103], s[2:3], v[170:171], v[102:103] op_sel_hi:[0,1,1]
	v_cvt_f32_ubyte1_e32 v169, v13
	v_cvt_f32_ubyte0_e32 v168, v13
	v_pk_fma_f32 v[98:99], s[40:41], v[168:169], v[98:99] op_sel_hi:[0,1,1]
	v_cvt_f32_ubyte1_e32 v171, v21
	v_cvt_f32_ubyte0_e32 v170, v21
	v_pk_fma_f32 v[98:99], s[38:39], v[170:171], v[98:99] op_sel_hi:[0,1,1]
	v_cvt_f32_ubyte1_e32 v169, v25
	v_cvt_f32_ubyte0_e32 v168, v25
	v_pk_fma_f32 v[98:99], s[42:43], v[168:169], v[98:99] op_sel_hi:[0,1,1]
	v_cvt_f32_ubyte1_e32 v171, v29
	v_cvt_f32_ubyte0_e32 v170, v29
	v_pk_fma_f32 v[98:99], s[2:3], v[170:171], v[98:99] op_sel_hi:[0,1,1]
	v_cvt_f32_ubyte3_e32 v169, v13
	v_cvt_f32_ubyte2_e32 v168, v13
	v_pk_fma_f32 v[100:101], s[40:41], v[168:169], v[100:101] op_sel_hi:[0,1,1]
	v_cvt_f32_ubyte3_e32 v171, v21
	v_cvt_f32_ubyte2_e32 v170, v21
	v_pk_fma_f32 v[100:101], s[38:39], v[170:171], v[100:101] op_sel_hi:[0,1,1]
	v_cvt_f32_ubyte3_e32 v169, v25
	v_cvt_f32_ubyte2_e32 v168, v25
	v_pk_fma_f32 v[100:101], s[42:43], v[168:169], v[100:101] op_sel_hi:[0,1,1]
	v_cvt_f32_ubyte3_e32 v171, v29
	v_cvt_f32_ubyte2_e32 v170, v29
	v_pk_fma_f32 v[100:101], s[2:3], v[170:171], v[100:101] op_sel_hi:[0,1,1]
	v_cvt_f32_ubyte1_e32 v169, v14
	v_cvt_f32_ubyte0_e32 v168, v14
	v_pk_fma_f32 v[94:95], s[40:41], v[168:169], v[94:95] op_sel_hi:[0,1,1]
	v_cvt_f32_ubyte1_e32 v171, v22
	v_cvt_f32_ubyte0_e32 v170, v22
	v_pk_fma_f32 v[94:95], s[38:39], v[170:171], v[94:95] op_sel_hi:[0,1,1]
	v_cvt_f32_ubyte1_e32 v169, v26
	v_cvt_f32_ubyte0_e32 v168, v26
	v_pk_fma_f32 v[94:95], s[42:43], v[168:169], v[94:95] op_sel_hi:[0,1,1]
	v_cvt_f32_ubyte1_e32 v171, v30
	v_cvt_f32_ubyte0_e32 v170, v30
	v_pk_fma_f32 v[94:95], s[2:3], v[170:171], v[94:95] op_sel_hi:[0,1,1]
	v_cvt_f32_ubyte3_e32 v169, v14
	v_cvt_f32_ubyte2_e32 v168, v14
	v_pk_fma_f32 v[96:97], s[40:41], v[168:169], v[96:97] op_sel_hi:[0,1,1]
	v_cvt_f32_ubyte3_e32 v171, v22
	v_cvt_f32_ubyte2_e32 v170, v22
	v_pk_fma_f32 v[96:97], s[38:39], v[170:171], v[96:97] op_sel_hi:[0,1,1]
	v_cvt_f32_ubyte3_e32 v169, v26
	v_cvt_f32_ubyte2_e32 v168, v26
	v_pk_fma_f32 v[96:97], s[42:43], v[168:169], v[96:97] op_sel_hi:[0,1,1]
	v_cvt_f32_ubyte3_e32 v171, v30
	v_cvt_f32_ubyte2_e32 v170, v30
	v_pk_fma_f32 v[96:97], s[2:3], v[170:171], v[96:97] op_sel_hi:[0,1,1]
	v_cvt_f32_ubyte1_e32 v169, v15
	v_cvt_f32_ubyte0_e32 v168, v15
	v_pk_fma_f32 v[90:91], s[40:41], v[168:169], v[90:91] op_sel_hi:[0,1,1]
	v_cvt_f32_ubyte1_e32 v171, v23
	v_cvt_f32_ubyte0_e32 v170, v23
	v_pk_fma_f32 v[90:91], s[38:39], v[170:171], v[90:91] op_sel_hi:[0,1,1]
	v_cvt_f32_ubyte1_e32 v169, v27
	v_cvt_f32_ubyte0_e32 v168, v27
	v_pk_fma_f32 v[90:91], s[42:43], v[168:169], v[90:91] op_sel_hi:[0,1,1]
	v_cvt_f32_ubyte1_e32 v171, v31
	v_cvt_f32_ubyte0_e32 v170, v31
	v_pk_fma_f32 v[90:91], s[2:3], v[170:171], v[90:91] op_sel_hi:[0,1,1]
	v_cvt_f32_ubyte3_e32 v169, v15
	v_cvt_f32_ubyte2_e32 v168, v15
	v_pk_fma_f32 v[92:93], s[40:41], v[168:169], v[92:93] op_sel_hi:[0,1,1]
	v_cvt_f32_ubyte3_e32 v171, v23
	v_cvt_f32_ubyte2_e32 v170, v23
	v_pk_fma_f32 v[92:93], s[38:39], v[170:171], v[92:93] op_sel_hi:[0,1,1]
	v_cvt_f32_ubyte3_e32 v169, v27
	v_cvt_f32_ubyte2_e32 v168, v27
	v_pk_fma_f32 v[92:93], s[42:43], v[168:169], v[92:93] op_sel_hi:[0,1,1]
	v_cvt_f32_ubyte3_e32 v171, v31
	v_cvt_f32_ubyte2_e32 v170, v31
	v_pk_fma_f32 v[92:93], s[2:3], v[170:171], v[92:93] op_sel_hi:[0,1,1]
	s_waitcnt vmcnt(0)
	v_mov_b64_e32 v[152:153], v[8:9]
	v_mov_b64_e32 v[154:155], v[10:11]
	v_mov_b64_e32 v[156:157], v[16:17]
	v_mov_b64_e32 v[158:159], v[18:19]
	v_mov_b64_e32 v[160:161], v[32:33]
	v_mov_b64_e32 v[162:163], v[34:35]
	v_mov_b64_e32 v[164:165], v[36:37]
	v_mov_b64_e32 v[166:167], v[38:39]
	v_mov_b64_e32 v[12:13], v[40:41]
	v_mov_b64_e32 v[14:15], v[42:43]
	v_mov_b64_e32 v[20:21], v[44:45]
	v_mov_b64_e32 v[22:23], v[46:47]
	v_mov_b64_e32 v[24:25], v[48:49]
	v_mov_b64_e32 v[26:27], v[50:51]
	v_mov_b64_e32 v[28:29], v[52:53]
	v_mov_b64_e32 v[30:31], v[54:55]
	v_mov_b32_e32 v140, v138
	v_mov_b32_e32 v141, v139
	s_mov_b32 s8, s76
	s_mov_b32 s9, s77
	s_mov_b32 s10, s78
	s_mov_b32 s11, s79
	s_cmp_eq_u32 s80, s33
	s_cbranch_scc1 .Lxp_nosw
	s_lshl_b32 s2, s33, 12
	v_add_u32_e32 v249, s2, v248
	ds_write_b128 v249, v[90:93]
	ds_write_b128 v249, v[94:97] offset:1024
	ds_write_b128 v249, v[98:101] offset:2048
	ds_write_b128 v249, v[102:105] offset:3072
	v_cmp_eq_u32_e32 vcc, s33, v60
	s_nop 1
	v_cndmask_b32_e32 v243, v243, v142, vcc
	s_lshl_b32 s2, s80, 12
	v_add_u32_e32 v249, s2, v248
	ds_read_b128 v[90:93], v249
	ds_read_b128 v[94:97], v249 offset:1024
	ds_read_b128 v[98:101], v249 offset:2048
	ds_read_b128 v[102:105], v249 offset:3072
	s_nop 0
	v_readlane_b32 s2, v243, s80
	v_readlane_b32 s3, v244, s80
	s_nop 1
	v_mov_b32_e32 v142, s2
	v_mov_b32_e32 v137, s3
	s_cmp_eq_u32 s80, 0
	s_cbranch_scc1 .Lxp_lxq0
	s_cmp_eq_u32 s80, 1
	s_cbranch_scc1 .Lxp_lxq1
	s_cmp_eq_u32 s80, 2
	s_cbranch_scc1 .Lxp_lxq2
	v_mov_b32_e32 v133, v236
	v_mov_b32_e32 v134, v237
	v_mov_b32_e32 v135, v238
	v_mov_b32_e32 v136, v239
	s_branch .Lxp_lxqd

.Lxp_lxqd:
	s_mov_b32 s33, s80
.Lxp_nosw:
	s_add_i32 s25, s25, 1
	s_cmp_lt_u32 s25, 0x80
	s_cbranch_scc1 .Lxp_unit
	s_waitcnt vmcnt(0) lgkmcnt(0)
	s_lshl_b32 s2, s33, 12
	v_add_u32_e32 v249, s2, v248
	ds_write_b128 v249, v[90:93]
	ds_write_b128 v249, v[94:97] offset:1024
	ds_write_b128 v249, v[98:101] offset:2048
	ds_write_b128 v249, v[102:105] offset:3072
	v_cmp_eq_u32_e32 vcc, s33, v60
	s_nop 1
	v_cndmask_b32_e32 v243, v243, v142, vcc
	v_readlane_b32 s76, v254, 34
	v_readlane_b32 s77, v254, 35
	s_mov_b32 s25, 0
.Lxp_out:
	s_lshl_b32 s2, s25, 12
	v_add_u32_e32 v249, s2, v248
	ds_read_b128 v[90:93], v249
	ds_read_b128 v[94:97], v249 offset:1024
	ds_read_b128 v[98:101], v249 offset:2048
	ds_read_b128 v[102:105], v249 offset:3072
	s_add_i32 s2, s32, s25
	s_lshl_b32 s3, s2, 11
	v_lshl_add_u32 v250, v60, 5, s3
	global_load_dwordx4 v[0:3], v250, s[16:17] offset:16
	global_load_dwordx4 v[4:7], v250, s[16:17]
	s_lshl_b32 s2, s2, 12
	v_lshl_add_u32 v251, v60, 6, s2
	v_readlane_b32 s3, v243, s25
	s_waitcnt vmcnt(0) lgkmcnt(0)
	v_mov_b32_e32 v142, s3
	v_lshlrev_b32_e32 v84, 16, v4
	v_and_b32_e32 v85, 0xffff0000, v4
	v_lshlrev_b32_e32 v86, 16, v5
	v_and_b32_e32 v87, 0xffff0000, v5
	v_lshlrev_b32_e32 v80, 16, v6
	v_and_b32_e32 v81, 0xffff0000, v6
	v_lshlrev_b32_e32 v82, 16, v7
	v_and_b32_e32 v83, 0xffff0000, v7
	v_lshlrev_b32_e32 v76, 16, v0
	v_and_b32_e32 v77, 0xffff0000, v0
	v_lshlrev_b32_e32 v78, 16, v1
	v_and_b32_e32 v79, 0xffff0000, v1
	v_lshlrev_b32_e32 v72, 16, v2
	v_and_b32_e32 v73, 0xffff0000, v2
	v_lshlrev_b32_e32 v74, 16, v3
	v_and_b32_e32 v75, 0xffff0000, v3
	v_pk_add_f32 v[8:9], v[104:105], v[84:85]
	v_pk_add_f32 v[10:11], v[102:103], v[86:87]
	v_fmac_f32_e32 v8, 0xc3000000, v142
	v_fmac_f32_e32 v9, 0xc3000000, v142
	v_fmac_f32_e32 v10, 0xc3000000, v142
	v_fmac_f32_e32 v11, 0xc3000000, v142
	global_store_dwordx4 v251, v[8:11], s[76:77]
	v_pk_add_f32 v[12:13], v[98:99], v[80:81]
	v_pk_add_f32 v[14:15], v[100:101], v[82:83]
	v_fmac_f32_e32 v12, 0xc3000000, v142
	v_fmac_f32_e32 v13, 0xc3000000, v142
	v_fmac_f32_e32 v14, 0xc3000000, v142
	v_fmac_f32_e32 v15, 0xc3000000, v142
	global_store_dwordx4 v251, v[12:15], s[76:77] offset:16
	v_pk_add_f32 v[16:17], v[94:95], v[76:77]
	v_pk_add_f32 v[18:19], v[96:97], v[78:79]
	v_fmac_f32_e32 v16, 0xc3000000, v142
	v_fmac_f32_e32 v17, 0xc3000000, v142
	v_fmac_f32_e32 v18, 0xc3000000, v142
	v_fmac_f32_e32 v19, 0xc3000000, v142
	global_store_dwordx4 v251, v[16:19], s[76:77] offset:32
	v_pk_add_f32 v[20:21], v[90:91], v[72:73]
	v_pk_add_f32 v[22:23], v[92:93], v[74:75]
	v_fmac_f32_e32 v20, 0xc3000000, v142
	v_fmac_f32_e32 v21, 0xc3000000, v142
	v_fmac_f32_e32 v22, 0xc3000000, v142
	v_fmac_f32_e32 v23, 0xc3000000, v142
	global_store_dwordx4 v251, v[20:23], s[76:77] offset:48
	s_add_i32 s25, s25, 1
	s_cmp_lt_u32 s25, 4
	s_cbranch_scc1 .Lxp_out
	s_waitcnt vmcnt(0)
	s_add_i32 s23, s23, 1
	s_cmp_lt_u32 s23, 8
	s_cbranch_scc1 .Lxp_sweep
	s_branch .LBB0_352

